# same as previous plus alignment anchor before the layer loop (P1 loop back at phase 12)
# speedup vs baseline: 1.0001x; 1.0001x over previous
.Lpb_done:
	.p2align 6
	s_nop 0
	s_nop 0
	s_nop 0
	s_nop 0
	s_nop 0
	s_nop 0
	s_nop 0
	s_nop 0
	s_nop 0
	s_nop 0
	s_nop 0
	s_nop 0
	s_nop 0
	s_nop 0
